# speedup vs baseline: 1.0242x; 1.0067x over previous
; #define GAS __attribute__((address_space(1)))
; __device__ __forceinline__ void attn_unit(LAS unsigned char* lds, bf16_t* Qm, const bf16_t* __restrict__ Kb, const bf16_t* __restrict__ Vt,
;                                           int b, int h, int qb, int lgS, float lam, float oscale, const float* __restrict__ subg, float* stash) {
;     ...
;     {
;         const float li = lam * inv;
;         int tq_ = threadIdx.x; asm volatile("" : "+v"(tq_)); const float* st_ = stash + tq_ * 64;
; #pragma unroll
;         for (int i = 0; i < 4; ++i)
; #pragma unroll
;             for (int r = 0; r < 16; r += 4) { const f32x4 sv = *(const GAS f32x4*)(st_ + i * 16 + r); o[i][r] = sv[0] - o[i][r] * li; o[i][r + 1] = sv[1] - o[i][r + 1] * li; o[i][r + 2] = sv[2] - o[i][r + 2] * li; o[i][r + 3] = sv[3] - o[i][r + 3] * li; }
;     }
;     float ssq = 0.f;
; #pragma unroll
;     for (int i = 0; i < 4; ++i)
; #pragma unroll
;         for (int r = 0; r < 16; ++r) ssq += o[i][r] * o[i][r];
;     ssq += __shfl_xor(ssq, 32);
;     const float rn = __builtin_amdgcn_rsqf(ssq * (1.0f / 128.0f) + SUBLN_EPS) * oscale;
.LBB0_331:
	v_mov_b32_e32 v65, v254
	v_mul_f32_e32 v124, s34, v64
	v_lshlrev_b32_e32 v66, 4, v65
	s_add_u32 s100, s66, 0x1c000
	s_addc_u32 s101, s67, 0
	global_load_dwordx4 v[96:99], v66, s[100:101]
	s_add_u32 s100, s66, 0x1e000
	s_addc_u32 s101, s67, 0
	global_load_dwordx4 v[120:123], v66, s[100:101]
	global_load_dwordx4 v[126:129], v66, s[66:67]
	s_add_u32 s100, s66, 0x2000
	s_addc_u32 s101, s67, 0
	global_load_dwordx4 v[130:133], v66, s[100:101]
	s_add_u32 s100, s66, 0x4000
	s_addc_u32 s101, s67, 0
	global_load_dwordx4 v[144:147], v66, s[100:101]
	s_add_u32 s100, s66, 0x6000
	s_addc_u32 s101, s67, 0
	global_load_dwordx4 v[148:151], v66, s[100:101]
	s_add_u32 s100, s66, 0x8000
	s_addc_u32 s101, s67, 0
	global_load_dwordx4 v[152:155], v66, s[100:101]
	s_add_u32 s100, s66, 0xa000
	s_addc_u32 s101, s67, 0
	global_load_dwordx4 v[156:159], v66, s[100:101]
	s_add_u32 s100, s66, 0xc000
	s_addc_u32 s101, s67, 0
	global_load_dwordx4 v[160:163], v66, s[100:101]
	s_add_u32 s100, s66, 0xe000
	s_addc_u32 s101, s67, 0
	global_load_dwordx4 v[164:167], v66, s[100:101]
	s_add_u32 s100, s66, 0x10000
	s_addc_u32 s101, s67, 0
	global_load_dwordx4 v[168:171], v66, s[100:101]
	s_add_u32 s100, s66, 0x12000
	s_addc_u32 s101, s67, 0
	global_load_dwordx4 v[116:119], v66, s[100:101]
	s_add_u32 s100, s66, 0x14000
	s_addc_u32 s101, s67, 0
	global_load_dwordx4 v[112:115], v66, s[100:101]
	s_add_u32 s100, s66, 0x16000
	s_addc_u32 s101, s67, 0
	global_load_dwordx4 v[108:111], v66, s[100:101]
	s_add_u32 s100, s66, 0x1a000
	s_addc_u32 s101, s67, 0
	global_load_dwordx4 v[100:103], v66, s[100:101]
	s_add_u32 s100, s66, 0x18000
	s_addc_u32 s101, s67, 0
	global_load_dwordx4 v[104:107], v66, s[100:101]
	v_mov_b32_e32 v64, v254
	v_mov_b64_e32 v[134:135], s[16:17]
	v_lshrrev_b32_e32 v66, 3, v64
	s_waitcnt vmcnt(16)
	v_and_b32_e32 v176, 4, v66
	v_ashrrev_i32_e32 v65, 1, v64
	v_lshlrev_b32_e32 v125, 2, v176
	v_and_b32_e32 v65, 0xffffffe0, v65
	v_add_u32_e32 v65, s4, v65
	v_and_or_b32 v136, v64, 31, v65
	s_lshl_b32 s90, s5, 1
	v_mad_i64_i32 v[134:135], s[4:5], v136, s72, v[134:135]
	global_load_dwordx4 v[80:83], v125, s[10:11]
	global_load_dwordx4 v[84:87], v125, s[10:11] offset:32
	global_load_dwordx4 v[88:91], v125, s[10:11] offset:64
	global_load_dwordx4 v[92:95], v125, s[10:11] offset:96
	global_load_dwordx4 v[64:67], v125, s[10:11] offset:128
	global_load_dwordx4 v[68:71], v125, s[10:11] offset:160
	global_load_dwordx4 v[72:75], v125, s[10:11] offset:192
	global_load_dwordx4 v[76:79], v125, s[10:11] offset:224
	v_lshl_add_u64 v[142:143], v[134:135], 0, s[90:91]
	v_lshlrev_b32_e32 v220, 1, v176
	s_add_i32 s64, s64, s48
	s_cmp_ge_i32 s64, s36
	s_waitcnt vmcnt(23)
	v_pk_fma_f32 v[98:99], v[26:27], v[124:125], v[98:99] op_sel_hi:[1,0,1] neg_lo:[1,0,0] neg_hi:[1,0,0]
	s_waitcnt vmcnt(22)
	v_pk_fma_f32 v[28:29], v[28:29], v[124:125], v[120:121] op_sel_hi:[1,0,1] neg_lo:[1,0,0] neg_hi:[1,0,0]
	s_waitcnt vmcnt(21)
	v_pk_fma_f32 v[140:141], v[0:1], v[124:125], v[126:127] op_sel_hi:[1,0,1] neg_lo:[1,0,0] neg_hi:[1,0,0]
	v_pk_fma_f32 v[138:139], v[2:3], v[124:125], v[128:129] op_sel_hi:[1,0,1] neg_lo:[1,0,0] neg_hi:[1,0,0]
	s_waitcnt vmcnt(20)
	v_pk_fma_f32 v[136:137], v[4:5], v[124:125], v[130:131] op_sel_hi:[1,0,1] neg_lo:[1,0,0] neg_hi:[1,0,0]
	s_waitcnt vmcnt(18)
	v_pk_fma_f32 v[128:129], v[12:13], v[124:125], v[148:149] op_sel_hi:[1,0,1] neg_lo:[1,0,0] neg_hi:[1,0,0]
	v_pk_fma_f32 v[126:127], v[14:15], v[124:125], v[150:151] op_sel_hi:[1,0,1] neg_lo:[1,0,0] neg_hi:[1,0,0]
	v_pk_fma_f32 v[130:131], v[10:11], v[124:125], v[146:147] op_sel_hi:[1,0,1] neg_lo:[1,0,0] neg_hi:[1,0,0]
	v_pk_mul_f32 v[146:147], v[136:137], v[136:137]
	s_waitcnt vmcnt(14)
	v_pk_fma_f32 v[12:13], v[62:63], v[124:125], v[166:167] op_sel_hi:[1,0,1] neg_lo:[1,0,0] neg_hi:[1,0,0]
	v_pk_mul_f32 v[62:63], v[140:141], v[140:141]
	v_pk_fma_f32 v[14:15], v[60:61], v[124:125], v[164:165] op_sel_hi:[1,0,1] neg_lo:[1,0,0] neg_hi:[1,0,0]
	v_pk_mul_f32 v[60:61], v[138:139], v[138:139]
	v_add_f32_e32 v62, v62, v63
	v_add_f32_e32 v60, v60, v62
	v_add_f32_e32 v60, v61, v60
	v_pk_fma_f32 v[134:135], v[6:7], v[124:125], v[132:133] op_sel_hi:[1,0,1] neg_lo:[1,0,0] neg_hi:[1,0,0]
	v_add_f32_e32 v60, v146, v60
	v_pk_fma_f32 v[132:133], v[8:9], v[124:125], v[144:145] op_sel_hi:[1,0,1] neg_lo:[1,0,0] neg_hi:[1,0,0]
	v_pk_mul_f32 v[144:145], v[134:135], v[134:135]
	v_add_f32_e32 v60, v147, v60
	v_add_f32_e32 v60, v144, v60
	v_pk_mul_f32 v[150:151], v[132:133], v[132:133]
	v_add_f32_e32 v60, v145, v60
	v_add_f32_e32 v60, v150, v60
	v_pk_mul_f32 v[148:149], v[130:131], v[130:131]
	v_add_f32_e32 v60, v151, v60
	v_add_f32_e32 v60, v148, v60
	v_pk_fma_f32 v[120:121], v[50:51], v[124:125], v[154:155] op_sel_hi:[1,0,1] neg_lo:[1,0,0] neg_hi:[1,0,0]
	v_pk_mul_f32 v[154:155], v[128:129], v[128:129]
	v_add_f32_e32 v60, v149, v60
	v_add_f32_e32 v60, v154, v60
	v_pk_fma_f32 v[26:27], v[30:31], v[124:125], v[122:123] op_sel_hi:[1,0,1] neg_lo:[1,0,0] neg_hi:[1,0,0]
	v_pk_fma_f32 v[122:123], v[48:49], v[124:125], v[152:153] op_sel_hi:[1,0,1] neg_lo:[1,0,0] neg_hi:[1,0,0]
	v_pk_mul_f32 v[152:153], v[126:127], v[126:127]
	v_add_f32_e32 v60, v155, v60
	v_add_f32_e32 v60, v152, v60
	v_pk_fma_f32 v[50:51], v[54:55], v[124:125], v[158:159] op_sel_hi:[1,0,1] neg_lo:[1,0,0] neg_hi:[1,0,0]
	v_pk_mul_f32 v[158:159], v[122:123], v[122:123]
	v_add_f32_e32 v60, v153, v60
	v_add_f32_e32 v60, v158, v60
	v_pk_fma_f32 v[52:53], v[52:53], v[124:125], v[156:157] op_sel_hi:[1,0,1] neg_lo:[1,0,0] neg_hi:[1,0,0]
	v_pk_mul_f32 v[156:157], v[120:121], v[120:121]
	v_add_f32_e32 v60, v159, v60
	v_add_f32_e32 v60, v156, v60
	v_pk_fma_f32 v[30:31], v[58:59], v[124:125], v[162:163] op_sel_hi:[1,0,1] neg_lo:[1,0,0] neg_hi:[1,0,0]
	v_pk_mul_f32 v[162:163], v[52:53], v[52:53]
	v_add_f32_e32 v60, v157, v60
	v_add_f32_e32 v60, v162, v60
	v_pk_fma_f32 v[48:49], v[56:57], v[124:125], v[160:161] op_sel_hi:[1,0,1] neg_lo:[1,0,0] neg_hi:[1,0,0]
	v_pk_mul_f32 v[160:161], v[50:51], v[50:51]
	v_add_f32_e32 v60, v163, v60
	v_add_f32_e32 v60, v160, v60
	v_pk_mul_f32 v[166:167], v[48:49], v[48:49]
	v_add_f32_e32 v60, v161, v60
	v_add_f32_e32 v60, v166, v60
	v_pk_mul_f32 v[164:165], v[30:31], v[30:31]
	v_add_f32_e32 v60, v167, v60
	v_add_f32_e32 v60, v164, v60
	s_waitcnt vmcnt(13)
; __device__ __forceinline__ unsigned cvtpk_s(float lo, float hi) { f32x2_t v = {lo, hi}; bf16x2_t b = __builtin_convertvector(v, bf16x2_t); return __builtin_bit_cast(unsigned, b); }
; __device__ __forceinline__ void attn_unit(LAS unsigned char* lds, bf16_t* Qm, const bf16_t* __restrict__ Kb, const bf16_t* __restrict__ Vt,
;                                           int b, int h, int qb, int lgS, float lam, float oscale, const float* __restrict__ subg, float* stash) {
;     ...
;     float ssq = 0.f;
; #pragma unroll
;     for (int i = 0; i < 4; ++i)
; #pragma unroll
;         for (int r = 0; r < 16; ++r) ssq += o[i][r] * o[i][r];
;     ssq += __shfl_xor(ssq, 32);
;     const float rn = __builtin_amdgcn_rsqf(ssq * (1.0f / 128.0f) + SUBLN_EPS) * oscale;
;     int te_ = threadIdx.x; asm volatile("" : "+v"(te_));
;     const int hi_e = (te_ >> 5) & 1;
;     bf16_t* op = Qm + (size_t)((b << lgS) + qb * 256 + (te_ >> 6) * 32 + (te_ & 31)) * MIXW + h * 128;
; #pragma unroll
;     for (int blk = 0; blk < 4; ++blk)
; #pragma unroll
;         for (int rg = 0; rg < 4; ++rg) {
;             const int d = 32 * blk + 8 * rg + 4 * hi_e;
;             const f32x4 g = *(const f32x4*)(subg + d);
;             u32x2 w; w.x = cvtpk_s(o[blk][4 * rg + 0] * rn * g[0], o[blk][4 * rg + 1] * rn * g[1]);
	v_pk_fma_f32 v[8:9], v[34:35], v[124:125], v[170:171] op_sel_hi:[1,0,1] neg_lo:[1,0,0] neg_hi:[1,0,0]
	v_pk_mul_f32 v[170:171], v[14:15], v[14:15]
	v_add_f32_e32 v60, v165, v60
	v_add_f32_e32 v60, v170, v60
	v_pk_fma_f32 v[10:11], v[32:33], v[124:125], v[168:169] op_sel_hi:[1,0,1] neg_lo:[1,0,0] neg_hi:[1,0,0]
	v_pk_mul_f32 v[168:169], v[12:13], v[12:13]
	v_add_f32_e32 v60, v171, v60
	v_add_f32_e32 v60, v168, v60
	v_pk_mul_f32 v[174:175], v[10:11], v[10:11]
	v_add_f32_e32 v60, v169, v60
	v_add_f32_e32 v60, v174, v60
	v_pk_mul_f32 v[172:173], v[8:9], v[8:9]
	v_add_f32_e32 v60, v175, v60
	s_waitcnt vmcnt(12)
	v_pk_fma_f32 v[36:37], v[36:37], v[124:125], v[116:117] op_sel_hi:[1,0,1] neg_lo:[1,0,0] neg_hi:[1,0,0]
	v_add_f32_e32 v60, v172, v60
	v_pk_mul_f32 v[116:117], v[36:37], v[36:37]
	v_add_f32_e32 v60, v173, v60
	v_pk_fma_f32 v[32:33], v[38:39], v[124:125], v[118:119] op_sel_hi:[1,0,1] neg_lo:[1,0,0] neg_hi:[1,0,0]
	v_add_f32_e32 v60, v116, v60
	v_pk_mul_f32 v[118:119], v[32:33], v[32:33]
	v_add_f32_e32 v60, v117, v60
	s_waitcnt vmcnt(11)
	v_pk_fma_f32 v[40:41], v[40:41], v[124:125], v[112:113] op_sel_hi:[1,0,1] neg_lo:[1,0,0] neg_hi:[1,0,0]
	v_add_f32_e32 v60, v118, v60
	v_pk_mul_f32 v[112:113], v[40:41], v[40:41]
	v_add_f32_e32 v60, v119, v60
	v_pk_fma_f32 v[34:35], v[42:43], v[124:125], v[114:115] op_sel_hi:[1,0,1] neg_lo:[1,0,0] neg_hi:[1,0,0]
	v_add_f32_e32 v60, v112, v60
	v_pk_mul_f32 v[114:115], v[34:35], v[34:35]
	v_add_f32_e32 v60, v113, v60
	s_waitcnt vmcnt(10)
	v_pk_fma_f32 v[42:43], v[44:45], v[124:125], v[108:109] op_sel_hi:[1,0,1] neg_lo:[1,0,0] neg_hi:[1,0,0]
	v_add_f32_e32 v60, v114, v60
	v_pk_mul_f32 v[108:109], v[42:43], v[42:43]
	v_add_f32_e32 v60, v115, v60
	v_pk_fma_f32 v[38:39], v[46:47], v[124:125], v[110:111] op_sel_hi:[1,0,1] neg_lo:[1,0,0] neg_hi:[1,0,0]
	v_add_f32_e32 v60, v108, v60
	v_pk_mul_f32 v[46:47], v[38:39], v[38:39]
	v_add_f32_e32 v60, v109, v60
	s_waitcnt vmcnt(8)
	v_pk_fma_f32 v[44:45], v[16:17], v[124:125], v[104:105] op_sel_hi:[1,0,1] neg_lo:[1,0,0] neg_hi:[1,0,0]
	v_add_f32_e32 v46, v46, v60
	v_pk_mul_f32 v[104:105], v[44:45], v[44:45]
	v_add_f32_e32 v46, v47, v46
	v_pk_fma_f32 v[18:19], v[18:19], v[124:125], v[106:107] op_sel_hi:[1,0,1] neg_lo:[1,0,0] neg_hi:[1,0,0]
	v_add_f32_e32 v46, v104, v46
	v_pk_mul_f32 v[106:107], v[18:19], v[18:19]
	v_add_f32_e32 v46, v105, v46
	v_pk_fma_f32 v[20:21], v[20:21], v[124:125], v[100:101] op_sel_hi:[1,0,1] neg_lo:[1,0,0] neg_hi:[1,0,0]
	v_add_f32_e32 v46, v106, v46
	v_pk_mul_f32 v[100:101], v[20:21], v[20:21]
	v_add_f32_e32 v46, v107, v46
	v_pk_fma_f32 v[16:17], v[22:23], v[124:125], v[102:103] op_sel_hi:[1,0,1] neg_lo:[1,0,0] neg_hi:[1,0,0]
	v_add_f32_e32 v46, v100, v46
	v_pk_mul_f32 v[102:103], v[16:17], v[16:17]
	v_add_f32_e32 v46, v101, v46
	v_pk_fma_f32 v[22:23], v[24:25], v[124:125], v[96:97] op_sel_hi:[1,0,1] neg_lo:[1,0,0] neg_hi:[1,0,0]
	v_add_f32_e32 v46, v102, v46
	v_pk_mul_f32 v[24:25], v[22:23], v[22:23]
	v_add_f32_e32 v46, v103, v46
	v_add_f32_e32 v24, v24, v46
	v_pk_mul_f32 v[58:59], v[98:99], v[98:99]
	v_add_f32_e32 v24, v25, v24
	v_add_f32_e32 v24, v58, v24
	v_pk_mul_f32 v[56:57], v[28:29], v[28:29]
	v_add_f32_e32 v24, v59, v24
	v_add_f32_e32 v24, v56, v24
	v_pk_mul_f32 v[54:55], v[26:27], v[26:27]
	v_add_f32_e32 v24, v57, v24
	v_add_f32_e32 v24, v54, v24
	v_add_f32_e32 v46, v55, v24
	ds_bpermute_b32 v47, v246, v46
	global_load_dwordx4 v[0:3], v125, s[10:11] offset:256
	global_load_dwordx4 v[4:7], v125, s[10:11] offset:288
	global_load_dwordx4 v[54:57], v125, s[10:11] offset:320
	global_load_dwordx4 v[58:61], v125, s[10:11] offset:352
	v_lshl_add_u64 v[24:25], v[142:143], 0, v[220:221]
	global_load_dwordx4 v[100:103], v125, s[10:11] offset:384
	global_load_dwordx4 v[104:107], v125, s[10:11] offset:416
	global_load_dwordx4 v[108:111], v125, s[10:11] offset:448
	s_waitcnt lgkmcnt(0)
	v_add_f32_e32 v46, v46, v47
	v_mov_b32_e32 v47, 0x3727c5ac
	v_fmamk_f32 v46, v46, 0x3c000000, v47
	v_rsq_f32_e32 v46, v46
	s_nop 0
	v_mul_f32_e32 v46, v247, v46
	v_pk_mul_f32 v[62:63], v[140:141], v[46:47] op_sel_hi:[1,0]
	v_pk_mul_f32 v[10:11], v[10:11], v[46:47] op_sel_hi:[1,0]
	s_waitcnt vmcnt(14)
	v_pk_mul_f32 v[62:63], v[80:81], v[62:63]
	v_pk_mul_f32 v[80:81], v[138:139], v[46:47] op_sel_hi:[1,0]
	v_cvt_pk_bf16_f32 v62, v62, v63
	v_pk_mul_f32 v[80:81], v[82:83], v[80:81]
	v_pk_mul_f32 v[8:9], v[8:9], v[46:47] op_sel_hi:[1,0]
	v_cvt_pk_bf16_f32 v63, v80, v81
	global_store_dwordx2 v[24:25], v[62:63], off
	v_pk_mul_f32 v[62:63], v[136:137], v[46:47] op_sel_hi:[1,0]
	v_pk_mul_f32 v[80:81], v[134:135], v[46:47] op_sel_hi:[1,0]
	s_waitcnt vmcnt(14)
; #define GAS __attribute__((address_space(1)))
; __device__ __forceinline__ unsigned cvtpk_s(float lo, float hi) { f32x2_t v = {lo, hi}; bf16x2_t b = __builtin_convertvector(v, bf16x2_t); return __builtin_bit_cast(unsigned, b); }
; __device__ __forceinline__ void attn_unit(LAS unsigned char* lds, bf16_t* Qm, const bf16_t* __restrict__ Kb, const bf16_t* __restrict__ Vt,
;                                           int b, int h, int qb, int lgS, float lam, float oscale, const float* __restrict__ subg, float* stash) {
;     ...
;     int te_ = threadIdx.x; asm volatile("" : "+v"(te_));
;     const int hi_e = (te_ >> 5) & 1;
;     bf16_t* op = Qm + (size_t)((b << lgS) + qb * 256 + (te_ >> 6) * 32 + (te_ & 31)) * MIXW + h * 128;
; #pragma unroll
;     for (int blk = 0; blk < 4; ++blk)
; #pragma unroll
;         for (int rg = 0; rg < 4; ++rg) {
;             const int d = 32 * blk + 8 * rg + 4 * hi_e;
;             const f32x4 g = *(const f32x4*)(subg + d);
;             u32x2 w; w.x = cvtpk_s(o[blk][4 * rg + 0] * rn * g[0], o[blk][4 * rg + 1] * rn * g[1]);
;             w.y = cvtpk_s(o[blk][4 * rg + 2] * rn * g[2], o[blk][4 * rg + 3] * rn * g[3]);
;             *(GAS u32x2*)(op + d) = w;
;         }
	v_pk_mul_f32 v[62:63], v[84:85], v[62:63]
	v_pk_mul_f32 v[80:81], v[86:87], v[80:81]
	v_cvt_pk_bf16_f32 v62, v62, v63
	v_cvt_pk_bf16_f32 v63, v80, v81
	global_store_dwordx2 v[24:25], v[62:63], off offset:16
	v_pk_mul_f32 v[62:63], v[132:133], v[46:47] op_sel_hi:[1,0]
	v_pk_mul_f32 v[80:81], v[130:131], v[46:47] op_sel_hi:[1,0]
	s_waitcnt vmcnt(14)
	v_pk_mul_f32 v[62:63], v[88:89], v[62:63]
	v_pk_mul_f32 v[80:81], v[90:91], v[80:81]
	v_cvt_pk_bf16_f32 v62, v62, v63
	v_cvt_pk_bf16_f32 v63, v80, v81
	global_store_dwordx2 v[24:25], v[62:63], off offset:32
	v_pk_mul_f32 v[62:63], v[128:129], v[46:47] op_sel_hi:[1,0]
	v_pk_mul_f32 v[80:81], v[126:127], v[46:47] op_sel_hi:[1,0]
	s_waitcnt vmcnt(14)
	v_pk_mul_f32 v[62:63], v[92:93], v[62:63]
	v_pk_mul_f32 v[80:81], v[94:95], v[80:81]
	v_cvt_pk_bf16_f32 v62, v62, v63
	v_cvt_pk_bf16_f32 v63, v80, v81
	global_load_dwordx4 v[80:83], v125, s[10:11] offset:480
	v_pk_mul_f32 v[52:53], v[52:53], v[46:47] op_sel_hi:[1,0]
	global_store_dwordx2 v[24:25], v[62:63], off offset:48
	v_pk_mul_f32 v[62:63], v[122:123], v[46:47] op_sel_hi:[1,0]
	v_pk_mul_f32 v[50:51], v[50:51], v[46:47] op_sel_hi:[1,0]
	s_waitcnt vmcnt(15)
	v_pk_mul_f32 v[62:63], v[64:65], v[62:63]
	v_pk_mul_f32 v[64:65], v[120:121], v[46:47] op_sel_hi:[1,0]
	v_pk_mul_f32 v[48:49], v[48:49], v[46:47] op_sel_hi:[1,0]
	v_pk_mul_f32 v[30:31], v[30:31], v[46:47] op_sel_hi:[1,0]
	v_pk_mul_f32 v[14:15], v[14:15], v[46:47] op_sel_hi:[1,0]
	v_pk_mul_f32 v[12:13], v[12:13], v[46:47] op_sel_hi:[1,0]
	v_pk_mul_f32 v[64:65], v[66:67], v[64:65]
	s_waitcnt vmcnt(14)
	v_pk_mul_f32 v[52:53], v[68:69], v[52:53]
	v_pk_mul_f32 v[50:51], v[70:71], v[50:51]
	s_waitcnt vmcnt(13)
	v_pk_mul_f32 v[48:49], v[72:73], v[48:49]
	v_pk_mul_f32 v[30:31], v[74:75], v[30:31]
	s_waitcnt vmcnt(12)
	v_pk_mul_f32 v[14:15], v[76:77], v[14:15]
	v_pk_mul_f32 v[12:13], v[78:79], v[12:13]
	v_cvt_pk_bf16_f32 v62, v62, v63
	v_cvt_pk_bf16_f32 v63, v64, v65
	v_cvt_pk_bf16_f32 v52, v52, v53
	v_cvt_pk_bf16_f32 v53, v50, v51
	v_cvt_pk_bf16_f32 v48, v48, v49
	v_cvt_pk_bf16_f32 v49, v30, v31
	v_cvt_pk_bf16_f32 v14, v14, v15
	v_cvt_pk_bf16_f32 v15, v12, v13
	global_store_dwordx2 v[24:25], v[62:63], off offset:64
	global_store_dwordx2 v[24:25], v[52:53], off offset:80
	global_store_dwordx2 v[24:25], v[48:49], off offset:96
	global_store_dwordx2 v[24:25], v[14:15], off offset:112
	s_waitcnt vmcnt(15)
	v_pk_mul_f32 v[0:1], v[0:1], v[10:11]
	v_pk_mul_f32 v[2:3], v[2:3], v[8:9]
	v_cvt_pk_bf16_f32 v0, v0, v1
	v_cvt_pk_bf16_f32 v1, v2, v3
	global_store_dwordx2 v[24:25], v[0:1], off offset:128
	v_pk_mul_f32 v[0:1], v[36:37], v[46:47] op_sel_hi:[1,0]
	v_pk_mul_f32 v[2:3], v[32:33], v[46:47] op_sel_hi:[1,0]
	s_waitcnt vmcnt(15)
	v_pk_mul_f32 v[0:1], v[4:5], v[0:1]
	v_pk_mul_f32 v[2:3], v[6:7], v[2:3]
	v_cvt_pk_bf16_f32 v0, v0, v1
	v_cvt_pk_bf16_f32 v1, v2, v3
	global_store_dwordx2 v[24:25], v[0:1], off offset:144
	v_pk_mul_f32 v[0:1], v[40:41], v[46:47] op_sel_hi:[1,0]
	v_pk_mul_f32 v[2:3], v[34:35], v[46:47] op_sel_hi:[1,0]
	s_waitcnt vmcnt(15)
	v_pk_mul_f32 v[0:1], v[54:55], v[0:1]
	v_pk_mul_f32 v[2:3], v[56:57], v[2:3]
	v_cvt_pk_bf16_f32 v0, v0, v1
	v_cvt_pk_bf16_f32 v1, v2, v3
	global_store_dwordx2 v[24:25], v[0:1], off offset:160
	v_pk_mul_f32 v[0:1], v[42:43], v[46:47] op_sel_hi:[1,0]
	v_pk_mul_f32 v[2:3], v[38:39], v[46:47] op_sel_hi:[1,0]
	s_waitcnt vmcnt(15)
	v_pk_mul_f32 v[0:1], v[58:59], v[0:1]
	v_pk_mul_f32 v[2:3], v[60:61], v[2:3]
	v_cvt_pk_bf16_f32 v0, v0, v1
	v_cvt_pk_bf16_f32 v1, v2, v3
	global_store_dwordx2 v[24:25], v[0:1], off offset:176
	v_pk_mul_f32 v[0:1], v[44:45], v[46:47] op_sel_hi:[1,0]
	v_pk_mul_f32 v[2:3], v[18:19], v[46:47] op_sel_hi:[1,0]
	s_waitcnt vmcnt(15)
	v_pk_mul_f32 v[0:1], v[100:101], v[0:1]
	v_pk_mul_f32 v[2:3], v[102:103], v[2:3]
	v_cvt_pk_bf16_f32 v0, v0, v1
	v_cvt_pk_bf16_f32 v1, v2, v3
	global_store_dwordx2 v[24:25], v[0:1], off offset:192
	v_pk_mul_f32 v[0:1], v[20:21], v[46:47] op_sel_hi:[1,0]
	v_pk_mul_f32 v[2:3], v[16:17], v[46:47] op_sel_hi:[1,0]
	s_waitcnt vmcnt(15)
	v_pk_mul_f32 v[0:1], v[104:105], v[0:1]
	v_pk_mul_f32 v[2:3], v[106:107], v[2:3]
	v_cvt_pk_bf16_f32 v0, v0, v1
	v_cvt_pk_bf16_f32 v1, v2, v3
	global_store_dwordx2 v[24:25], v[0:1], off offset:208
	v_pk_mul_f32 v[0:1], v[22:23], v[46:47] op_sel_hi:[1,0]
	v_pk_mul_f32 v[2:3], v[98:99], v[46:47] op_sel_hi:[1,0]
	s_waitcnt vmcnt(15)
	v_pk_mul_f32 v[0:1], v[108:109], v[0:1]
	v_pk_mul_f32 v[2:3], v[110:111], v[2:3]
	v_cvt_pk_bf16_f32 v0, v0, v1
	v_cvt_pk_bf16_f32 v1, v2, v3
	global_store_dwordx2 v[24:25], v[0:1], off offset:224
	v_pk_mul_f32 v[0:1], v[28:29], v[46:47] op_sel_hi:[1,0]
	v_pk_mul_f32 v[2:3], v[26:27], v[46:47] op_sel_hi:[1,0]
	s_waitcnt vmcnt(12)
	v_pk_mul_f32 v[0:1], v[80:81], v[0:1]
	v_pk_mul_f32 v[2:3], v[82:83], v[2:3]
	v_cvt_pk_bf16_f32 v0, v0, v1
	v_cvt_pk_bf16_f32 v1, v2, v3
	global_store_dwordx2 v[24:25], v[0:1], off offset:240
	s_cbranch_scc1 .LBB0_351

; #define LAS __attribute__((address_space(3)))
; #define GAS __attribute__((address_space(1)))
; __device__ __forceinline__ void attn_unit(LAS unsigned char* lds, bf16_t* Qm, const bf16_t* __restrict__ Kb, const bf16_t* __restrict__ Vt,
;                                           int b, int h, int qb, int lgS, float lam, float oscale, const float* __restrict__ subg, float* stash) {
;     ...
;         {
; #pragma unroll
;             for (int blk = 0; blk < 4; ++blk) o[blk] = __builtin_amdgcn_mfma_f32_32x32x16_bf16(vfa[blk], __builtin_bit_cast(bf16x8, pk[0]), o[blk], 0, 0, 0);
; #pragma unroll
;             for (int ks = 1; ks < 4; ++ks)
; #pragma unroll
;                 for (int blk = 0; blk < 4; ++blk) {
;                     const bf16x8 vf = *(const LAS bf16x8*)(lds + vs0 + vr + blk * 32 * VP + ks * 32);
;                     o[blk] = __builtin_amdgcn_mfma_f32_32x32x16_bf16(vf, __builtin_bit_cast(bf16x8, pk[ks]), o[blk], 0, 0, 0);
;                 }
;         }
;         __syncthreads();
;         lrun += __shfl_xor(lrun, 32);
;         inv = 1.0f / lrun;
;         if (c == 0) {
;             int tq_ = threadIdx.x; asm volatile("" : "+v"(tq_)); float* st_ = stash + tq_ * 64;
; #pragma unroll
;             for (int i = 0; i < 4; ++i)
; #pragma unroll
;                 for (int r = 0; r < 16; r += 4) *(GAS f32x4*)(st_ + i * 16 + r) = (f32x4){o[i][r] * inv, o[i][r + 1] * inv, o[i][r + 2] * inv, o[i][r + 3] * inv};
;         }
.LBB0_349:
	v_mfma_f32_32x32x16_bf16 v[0:15], v[196:199], v[200:203], v[0:15]
	v_add_u32_e32 v72, s25, v220
	ds_read_b128 v[64:67], v72 offset:25376
	ds_read_b128 v[68:71], v72 offset:25408
	s_waitcnt lgkmcnt(1)
	v_mfma_f32_32x32x16_bf16 v[0:15], v[64:67], v[180:183], v[0:15]
	ds_read_b128 v[64:67], v72 offset:29984
	v_mfma_f32_32x32x16_bf16 v[48:63], v[192:195], v[200:203], v[48:63]
	s_waitcnt lgkmcnt(0)
	v_mfma_f32_32x32x16_bf16 v[48:63], v[64:67], v[180:183], v[48:63]
	ds_read_b128 v[64:67], v72 offset:34592
	v_mfma_f32_32x32x16_bf16 v[32:47], v[188:191], v[200:203], v[32:47]
	s_waitcnt lgkmcnt(0)
	v_mfma_f32_32x32x16_bf16 v[32:47], v[64:67], v[180:183], v[32:47]
	ds_read_b128 v[64:67], v72 offset:39200
	v_mfma_f32_32x32x16_bf16 v[16:31], v[184:187], v[200:203], v[16:31]
	s_waitcnt lgkmcnt(0)
	v_mfma_f32_32x32x16_bf16 v[16:31], v[64:67], v[180:183], v[16:31]
	ds_read_b128 v[64:67], v72 offset:30016
	s_waitcnt lgkmcnt(0)
	v_mfma_f32_32x32x16_bf16 v[48:63], v[64:67], v[172:175], v[48:63]
	ds_read_b128 v[64:67], v72 offset:34624
	s_waitcnt lgkmcnt(0)
	v_mfma_f32_32x32x16_bf16 v[32:47], v[64:67], v[172:175], v[32:47]
	ds_read_b128 v[64:67], v72 offset:39232
	s_waitcnt lgkmcnt(0)
	v_mfma_f32_32x32x16_bf16 v[16:31], v[64:67], v[172:175], v[16:31]
	ds_read_b128 v[64:67], v72 offset:25440
	v_mfma_f32_32x32x16_bf16 v[0:15], v[68:71], v[172:175], v[0:15]
	s_waitcnt lgkmcnt(0)
	v_mfma_f32_32x32x16_bf16 v[0:15], v[64:67], v[164:167], v[0:15]
	ds_read_b128 v[64:67], v72 offset:30048
	s_waitcnt lgkmcnt(0)
	v_mfma_f32_32x32x16_bf16 v[48:63], v[64:67], v[164:167], v[48:63]
	ds_read_b128 v[64:67], v72 offset:34656
	s_waitcnt lgkmcnt(0)
	v_mfma_f32_32x32x16_bf16 v[32:47], v[64:67], v[164:167], v[32:47]
	ds_read_b128 v[64:67], v72 offset:39264
	s_waitcnt lgkmcnt(0)
	s_barrier
	v_mfma_f32_32x32x16_bf16 v[16:31], v[64:67], v[164:167], v[16:31]
	ds_bpermute_b32 v64, v246, v249
	s_waitcnt lgkmcnt(0)
	v_add_f32_e32 v64, v249, v64
	v_div_scale_f32 v65, s[28:29], v64, v64, 1.0
	v_rcp_f32_e32 v66, v65
	s_mov_b64 s[28:29], -1
	v_fma_f32 v67, -v65, v66, 1.0
	v_fmac_f32_e32 v66, v67, v66
	v_div_scale_f32 v67, vcc, 1.0, v64, 1.0
	v_mul_f32_e32 v68, v67, v66
	v_fma_f32 v69, -v65, v68, v67
	v_fmac_f32_e32 v68, v69, v66
	v_fma_f32 v65, -v65, v68, v67
	v_div_fmas_f32 v65, v65, v66, v68
	v_div_fixup_f32 v64, v65, v64, 1.0
	s_and_b64 vcc, exec, s[26:27]
	s_cbranch_vccz .LBB0_333
	v_mov_b32_e32 v65, v254
	s_mov_b64 s[28:29], 0
	v_lshlrev_b32_e32 v70, 4, v65
	v_pk_mul_f32 v[66:67], v[0:1], v[64:65] op_sel_hi:[1,0]
	v_pk_mul_f32 v[68:69], v[2:3], v[64:65] op_sel_hi:[1,0]
	global_store_dwordx4 v70, v[66:69], s[66:67]
	s_nop 1
	v_pk_mul_f32 v[66:67], v[4:5], v[64:65] op_sel_hi:[1,0]
	v_pk_mul_f32 v[68:69], v[6:7], v[64:65] op_sel_hi:[1,0]
	s_add_u32 s100, s66, 0x2000
	s_addc_u32 s101, s67, 0
	global_store_dwordx4 v70, v[66:69], s[100:101]
	s_nop 1
	v_pk_mul_f32 v[66:67], v[8:9], v[64:65] op_sel_hi:[1,0]
	v_pk_mul_f32 v[68:69], v[10:11], v[64:65] op_sel_hi:[1,0]
	s_add_u32 s100, s66, 0x4000
	s_addc_u32 s101, s67, 0
	global_store_dwordx4 v70, v[66:69], s[100:101]
	s_nop 1
	v_pk_mul_f32 v[66:67], v[12:13], v[64:65] op_sel_hi:[1,0]
	v_pk_mul_f32 v[68:69], v[14:15], v[64:65] op_sel_hi:[1,0]
	s_add_u32 s100, s66, 0x6000
	s_addc_u32 s101, s67, 0
	global_store_dwordx4 v70, v[66:69], s[100:101]
	s_nop 1
	v_pk_mul_f32 v[66:67], v[48:49], v[64:65] op_sel_hi:[1,0]
	v_pk_mul_f32 v[68:69], v[50:51], v[64:65] op_sel_hi:[1,0]
	s_add_u32 s100, s66, 0x8000
	s_addc_u32 s101, s67, 0
	global_store_dwordx4 v70, v[66:69], s[100:101]
	s_nop 1
	v_pk_mul_f32 v[66:67], v[52:53], v[64:65] op_sel_hi:[1,0]
	v_pk_mul_f32 v[68:69], v[54:55], v[64:65] op_sel_hi:[1,0]
	s_add_u32 s100, s66, 0xa000
	s_addc_u32 s101, s67, 0
	global_store_dwordx4 v70, v[66:69], s[100:101]
	s_nop 1
	v_pk_mul_f32 v[66:67], v[56:57], v[64:65] op_sel_hi:[1,0]
	v_pk_mul_f32 v[68:69], v[58:59], v[64:65] op_sel_hi:[1,0]
	s_add_u32 s100, s66, 0xc000
	s_addc_u32 s101, s67, 0
	global_store_dwordx4 v70, v[66:69], s[100:101]
	s_nop 1
	v_pk_mul_f32 v[66:67], v[60:61], v[64:65] op_sel_hi:[1,0]
	v_pk_mul_f32 v[68:69], v[62:63], v[64:65] op_sel_hi:[1,0]
	s_add_u32 s100, s66, 0xe000
	s_addc_u32 s101, s67, 0
	global_store_dwordx4 v70, v[66:69], s[100:101]
	s_nop 1
	v_pk_mul_f32 v[66:67], v[32:33], v[64:65] op_sel_hi:[1,0]
	v_pk_mul_f32 v[68:69], v[34:35], v[64:65] op_sel_hi:[1,0]
	s_add_u32 s100, s66, 0x10000
	s_addc_u32 s101, s67, 0
	global_store_dwordx4 v70, v[66:69], s[100:101]
	s_nop 1
	v_pk_mul_f32 v[66:67], v[36:37], v[64:65] op_sel_hi:[1,0]
	v_pk_mul_f32 v[68:69], v[38:39], v[64:65] op_sel_hi:[1,0]
	s_add_u32 s100, s66, 0x12000
	s_addc_u32 s101, s67, 0
	global_store_dwordx4 v70, v[66:69], s[100:101]
	s_nop 1
	v_pk_mul_f32 v[66:67], v[40:41], v[64:65] op_sel_hi:[1,0]
	v_pk_mul_f32 v[68:69], v[42:43], v[64:65] op_sel_hi:[1,0]
	s_add_u32 s100, s66, 0x14000
	s_addc_u32 s101, s67, 0
	global_store_dwordx4 v70, v[66:69], s[100:101]
	s_nop 1
	v_pk_mul_f32 v[66:67], v[44:45], v[64:65] op_sel_hi:[1,0]
	v_pk_mul_f32 v[68:69], v[46:47], v[64:65] op_sel_hi:[1,0]
	s_add_u32 s100, s66, 0x16000
	s_addc_u32 s101, s67, 0
	global_store_dwordx4 v70, v[66:69], s[100:101]
	s_nop 1
	v_pk_mul_f32 v[66:67], v[16:17], v[64:65] op_sel_hi:[1,0]
	v_pk_mul_f32 v[68:69], v[18:19], v[64:65] op_sel_hi:[1,0]
	s_add_u32 s100, s66, 0x18000
	s_addc_u32 s101, s67, 0
	global_store_dwordx4 v70, v[66:69], s[100:101]
	s_nop 1
	v_pk_mul_f32 v[66:67], v[20:21], v[64:65] op_sel_hi:[1,0]
	v_pk_mul_f32 v[68:69], v[22:23], v[64:65] op_sel_hi:[1,0]
	s_add_u32 s100, s66, 0x1a000
	s_addc_u32 s101, s67, 0
	global_store_dwordx4 v70, v[66:69], s[100:101]
	s_nop 1
	v_pk_mul_f32 v[66:67], v[24:25], v[64:65] op_sel_hi:[1,0]
	v_pk_mul_f32 v[68:69], v[26:27], v[64:65] op_sel_hi:[1,0]
	s_add_u32 s100, s66, 0x1c000
	s_addc_u32 s101, s67, 0
	global_store_dwordx4 v70, v[66:69], s[100:101]
	s_nop 1
	v_pk_mul_f32 v[66:67], v[28:29], v[64:65] op_sel_hi:[1,0]
	v_pk_mul_f32 v[68:69], v[30:31], v[64:65] op_sel_hi:[1,0]
	s_add_u32 s100, s66, 0x1e000
	s_addc_u32 s101, s67, 0
	global_store_dwordx4 v70, v[66:69], s[100:101]
	s_branch .LBB0_333
